# W2 weight transposes for FFN instances 1-3 moved from prologue to idle CUs in FFN-up tail rounds
# speedup vs baseline: 1.0469x; 1.0026x over previous
; __device__ __forceinline__ void prologue(const Params& p, LAS unsigned char* lds) {
;     ...
;         for (int it = gw; it < NITEMS; it += NGW) {
;             int r = it;
;             if (r < 4 * I_W1) { const int mi = r / I_W1; r -= mi * I_W1; const int kb = r / 176, nb = r % 176;
;                 transpose_item(p.in[I_FFNWIN] + (size_t)mi * D * NFF1, D, NFF1, (bf16_t*)(ws + WS_W1T + mi * SZ_W1T), paired_src(nb * 32, DFF), nb * 32, kb * 64, scr, lane); continue; }
;             r -= 4 * I_W1;
;             if (r < 4 * I_W2) { const int mi = r / I_W2; r -= mi * I_W2; const int kb = r / 32, nb = r % 32;
;                 transpose_item(p.in[I_FFNWOUT] + (size_t)mi * DFF * D, DFF, D, (bf16_t*)(ws + WS_W2T + mi * SZ_W2T), nb * 32, nb * 32, kb * 64, scr, lane); continue; }
.LBB0_30:
	s_or_b64 exec, exec, s[8:9]
	v_add_u32_e32 v39, s94, v39
	v_add_u32_e32 v28, s18, v28
	v_add_u32_e32 v29, s19, v29
	v_mov_b32_e32 v255, 0x317f
	v_cmp_lt_u32_e32 vcc, v255, v39
	v_mov_b32_e32 v255, 0x4200
	v_cmp_gt_u32_e64 s[98:99], v255, v39
	s_and_b64 vcc, vcc, s[98:99]
	s_cmpk_eq_u32 s82, 0x100
	s_cselect_b64 s[98:99], -1, 0
	s_and_b64 vcc, vcc, s[98:99]
	v_cndmask_b32_e64 v255, 0, 1, vcc
	v_mul_u32_u24_e32 v254, 0x1080, v255
	v_add_u32_e32 v39, v39, v254
	v_mul_u32_u24_e32 v254, 0x21000, v255
	v_add_u32_e32 v28, v28, v254
	v_mul_u32_u24_e32 v254, 0x2100, v255
	v_add_u32_e32 v29, v29, v254
	v_cmp_lt_i32_e32 vcc, s40, v39
	s_or_b64 s[6:7], vcc, s[6:7]
	s_andn2_b64 exec, exec, s[6:7]
	s_cbranch_execz .LBB0_49

; #define LAS __attribute__((address_space(3)))
; __device__ __forceinline__ unsigned cvt_pk_bf16(float lo, float hi) { unsigned r; asm volatile("v_cvt_pk_bf16_f32 %0, %1, %2" : "=v"(r) : "v"(lo), "v"(hi)); return r; }
; #define ST16(grp, p, v) do { if ((NTG >> (grp)) & 1) NT16(p, v); else PL16(p, v); } while (0)
; __device__ __forceinline__ void transpose_item(const float* W, int K, int N, bf16_t* WT, int n0src, int n0dst, int k0, LAS float* scr, int lane) {
;     float v[32];
; #pragma unroll
;     for (int i = 0; i < 32; ++i) { const int kk = 2 * i + (lane >> 5); v[i] = W[(size_t)(k0 + kk) * N + n0src + (lane & 31)]; }
; #pragma unroll
;     for (int i = 0; i < 32; ++i) { const int kk = 2 * i + (lane >> 5); scr[kk * 33 + (lane & 31)] = v[i]; }
;     asm volatile("s_waitcnt lgkmcnt(0)" ::: "memory");
;     const int c = lane & 7;
; #pragma unroll
;     for (int j = 0; j < 4; ++j) { const int n = (lane >> 3) + 8 * j; const LAS float* s = scr + (8 * c) * 33 + n;
;         u32x4 o; o.x = cvt_pk_bf16(s[0 * 33], s[1 * 33]); o.y = cvt_pk_bf16(s[2 * 33], s[3 * 33]); o.z = cvt_pk_bf16(s[4 * 33], s[5 * 33]); o.w = cvt_pk_bf16(s[6 * 33], s[7 * 33]);
;         ST16(6, WT + (size_t)(n0dst + n) * K + k0 + 8 * c, o); }
;     asm volatile("s_waitcnt lgkmcnt(0)" ::: "memory");
; }
; __device__ __forceinline__ void prologue(const Params& p, LAS unsigned char* lds) {
;     ...
;             if (r < 4 * I_W2) { const int mi = r / I_W2; r -= mi * I_W2; const int kb = r / 32, nb = r % 32;
;                 transpose_item(p.in[I_FFNWOUT] + (size_t)mi * DFF * D, DFF, D, (bf16_t*)(ws + WS_W2T + mi * SZ_W2T), nb * 32, nb * 32, kb * 64, scr, lane); continue; }
.LBB0_976:
	s_waitcnt vmcnt(0)
	s_barrier
	s_cmpk_lg_u32 s78, 0x100
	s_cbranch_scc1 .Ltr_done_a
	s_cmpk_lt_u32 s68, 0x80
	s_cbranch_scc1 .Ltr_done_a
	s_mov_b64 s[38:39], exec
	s_mov_b64 exec, -1
	v_readfirstlane_b32 s99, v176
	s_lshr_b32 s99, s99, 6
	s_sub_i32 s98, s68, 0x80
	s_lshl_b32 s98, s98, 3
	s_add_i32 s98, s98, s99
	s_lshl_b32 s99, s99, 14
	v_and_b32_e32 v16, 63, v176
	v_and_b32_e32 v17, 31, v16
	v_lshrrev_b32_e32 v18, 5, v16
	v_mul_u32_u24_e32 v19, 0x84, v18
	v_lshl_add_u32 v19, v17, 2, v19
	v_add_u32_e32 v19, s99, v19
	v_and_b32_e32 v20, 7, v16
	v_lshrrev_b32_e32 v21, 3, v16
	v_mul_u32_u24_e32 v22, 0x420, v20
	v_lshl_add_u32 v22, v21, 2, v22
	v_add_u32_e32 v22, s99, v22
	v_lshlrev_b32_e32 v23, 12, v18
	v_lshl_add_u32 v23, v17, 2, v23
	v_mul_u32_u24_e32 v24, 0x1600, v21
	v_lshl_add_u32 v24, v20, 4, v24
	v_readlane_b32 s32, v253, 0
	v_readlane_b32 s33, v253, 1
	s_add_u32 s32, s32, 0xb00000
	s_addc_u32 s33, s33, 0
	s_add_u32 s34, s76, 0x3380000
	s_addc_u32 s35, s77, 0
.Ltr_loop_a:
	s_lshr_b32 s100, s98, 5
	s_and_b32 s101, s98, 31
	s_lshl_b32 s0, s100, 18
	s_lshl_b32 s1, s101, 7
	s_add_u32 s0, s0, s1
	s_add_u32 s0, s32, s0
	s_addc_u32 s1, s33, 0
	global_load_dword v32, v23, s[0:1] nt
	s_add_u32 s0, s0, 0x2000
	s_addc_u32 s1, s1, 0
	global_load_dword v33, v23, s[0:1] nt
	s_add_u32 s0, s0, 0x2000
	s_addc_u32 s1, s1, 0
	global_load_dword v34, v23, s[0:1] nt
	s_add_u32 s0, s0, 0x2000
	s_addc_u32 s1, s1, 0
	global_load_dword v35, v23, s[0:1] nt
	s_add_u32 s0, s0, 0x2000
	s_addc_u32 s1, s1, 0
	global_load_dword v36, v23, s[0:1] nt
	s_add_u32 s0, s0, 0x2000
	s_addc_u32 s1, s1, 0
	global_load_dword v37, v23, s[0:1] nt
	s_add_u32 s0, s0, 0x2000
	s_addc_u32 s1, s1, 0
	global_load_dword v38, v23, s[0:1] nt
	s_add_u32 s0, s0, 0x2000
	s_addc_u32 s1, s1, 0
	global_load_dword v39, v23, s[0:1] nt
	s_add_u32 s0, s0, 0x2000
	s_addc_u32 s1, s1, 0
	global_load_dword v40, v23, s[0:1] nt
	s_add_u32 s0, s0, 0x2000
	s_addc_u32 s1, s1, 0
	global_load_dword v41, v23, s[0:1] nt
	s_add_u32 s0, s0, 0x2000
	s_addc_u32 s1, s1, 0
	global_load_dword v42, v23, s[0:1] nt
	s_add_u32 s0, s0, 0x2000
	s_addc_u32 s1, s1, 0
	global_load_dword v43, v23, s[0:1] nt
	s_add_u32 s0, s0, 0x2000
	s_addc_u32 s1, s1, 0
	global_load_dword v44, v23, s[0:1] nt
	s_add_u32 s0, s0, 0x2000
	s_addc_u32 s1, s1, 0
	global_load_dword v45, v23, s[0:1] nt
	s_add_u32 s0, s0, 0x2000
	s_addc_u32 s1, s1, 0
	global_load_dword v46, v23, s[0:1] nt
	s_add_u32 s0, s0, 0x2000
	s_addc_u32 s1, s1, 0
	global_load_dword v47, v23, s[0:1] nt
	s_add_u32 s0, s0, 0x2000
	s_addc_u32 s1, s1, 0
	global_load_dword v48, v23, s[0:1] nt
	s_add_u32 s0, s0, 0x2000
	s_addc_u32 s1, s1, 0
	global_load_dword v49, v23, s[0:1] nt
	s_add_u32 s0, s0, 0x2000
	s_addc_u32 s1, s1, 0
	global_load_dword v50, v23, s[0:1] nt
	s_add_u32 s0, s0, 0x2000
	s_addc_u32 s1, s1, 0
	global_load_dword v51, v23, s[0:1] nt
	s_add_u32 s0, s0, 0x2000
	s_addc_u32 s1, s1, 0
	global_load_dword v52, v23, s[0:1] nt
	s_add_u32 s0, s0, 0x2000
	s_addc_u32 s1, s1, 0
	global_load_dword v53, v23, s[0:1] nt
	s_add_u32 s0, s0, 0x2000
	s_addc_u32 s1, s1, 0
	global_load_dword v54, v23, s[0:1] nt
	s_add_u32 s0, s0, 0x2000
	s_addc_u32 s1, s1, 0
	global_load_dword v55, v23, s[0:1] nt
	s_add_u32 s0, s0, 0x2000
	s_addc_u32 s1, s1, 0
	global_load_dword v56, v23, s[0:1] nt
	s_add_u32 s0, s0, 0x2000
	s_addc_u32 s1, s1, 0
	global_load_dword v57, v23, s[0:1] nt
	s_add_u32 s0, s0, 0x2000
	s_addc_u32 s1, s1, 0
	global_load_dword v58, v23, s[0:1] nt
	s_add_u32 s0, s0, 0x2000
	s_addc_u32 s1, s1, 0
	global_load_dword v59, v23, s[0:1] nt
	s_add_u32 s0, s0, 0x2000
	s_addc_u32 s1, s1, 0
	global_load_dword v60, v23, s[0:1] nt
	s_add_u32 s0, s0, 0x2000
	s_addc_u32 s1, s1, 0
	global_load_dword v61, v23, s[0:1] nt
	s_add_u32 s0, s0, 0x2000
	s_addc_u32 s1, s1, 0
	global_load_dword v62, v23, s[0:1] nt
	s_add_u32 s0, s0, 0x2000
	s_addc_u32 s1, s1, 0
	global_load_dword v63, v23, s[0:1] nt
	s_waitcnt vmcnt(31)
	ds_write_b32 v19, v32
	s_waitcnt vmcnt(30)
	ds_write_b32 v19, v33 offset:264
	s_waitcnt vmcnt(29)
	ds_write_b32 v19, v34 offset:528
	s_waitcnt vmcnt(28)
	ds_write_b32 v19, v35 offset:792
	s_waitcnt vmcnt(27)
	ds_write_b32 v19, v36 offset:1056
	s_waitcnt vmcnt(26)
	ds_write_b32 v19, v37 offset:1320
	s_waitcnt vmcnt(25)
	ds_write_b32 v19, v38 offset:1584
	s_waitcnt vmcnt(24)
	ds_write_b32 v19, v39 offset:1848
	s_waitcnt vmcnt(23)
	ds_write_b32 v19, v40 offset:2112
	s_waitcnt vmcnt(22)
	ds_write_b32 v19, v41 offset:2376
	s_waitcnt vmcnt(21)
	ds_write_b32 v19, v42 offset:2640
	s_waitcnt vmcnt(20)
	ds_write_b32 v19, v43 offset:2904
	s_waitcnt vmcnt(19)
	ds_write_b32 v19, v44 offset:3168
	s_waitcnt vmcnt(18)
; #define LAS __attribute__((address_space(3)))
; __device__ __forceinline__ unsigned cvt_pk_bf16(float lo, float hi) { unsigned r; asm volatile("v_cvt_pk_bf16_f32 %0, %1, %2" : "=v"(r) : "v"(lo), "v"(hi)); return r; }
; #define ST16(grp, p, v) do { if ((NTG >> (grp)) & 1) NT16(p, v); else PL16(p, v); } while (0)
; __device__ __forceinline__ void xcd_barrier(const XcdBarrier& b) {
;     asm volatile("s_waitcnt vmcnt(0)" ::: "memory");
;     __syncthreads();
;     if (threadIdx.x == 0) {
;         unsigned* bar = b.bar;
;         __builtin_amdgcn_s_waitcnt(0);
;         unsigned nloc = b.st[0], nx = b.st[1];
;         if (nloc == 0u) { xcd_barrier_complete(bar, b.x, nloc, nx); b.st[0] = nloc; b.st[1] = nx; }
; __device__ __forceinline__ void transpose_item(const float* W, int K, int N, bf16_t* WT, int n0src, int n0dst, int k0, LAS float* scr, int lane) {
;     float v[32];
; #pragma unroll
;     for (int i = 0; i < 32; ++i) { const int kk = 2 * i + (lane >> 5); v[i] = W[(size_t)(k0 + kk) * N + n0src + (lane & 31)]; }
; #pragma unroll
;     for (int i = 0; i < 32; ++i) { const int kk = 2 * i + (lane >> 5); scr[kk * 33 + (lane & 31)] = v[i]; }
;     asm volatile("s_waitcnt lgkmcnt(0)" ::: "memory");
;     const int c = lane & 7;
; #pragma unroll
;     for (int j = 0; j < 4; ++j) { const int n = (lane >> 3) + 8 * j; const LAS float* s = scr + (8 * c) * 33 + n;
;         u32x4 o; o.x = cvt_pk_bf16(s[0 * 33], s[1 * 33]); o.y = cvt_pk_bf16(s[2 * 33], s[3 * 33]); o.z = cvt_pk_bf16(s[4 * 33], s[5 * 33]); o.w = cvt_pk_bf16(s[6 * 33], s[7 * 33]);
;         ST16(6, WT + (size_t)(n0dst + n) * K + k0 + 8 * c, o); }
;     asm volatile("s_waitcnt lgkmcnt(0)" ::: "memory");
; }
	ds_write_b32 v19, v45 offset:3432
	s_waitcnt vmcnt(17)
	ds_write_b32 v19, v46 offset:3696
	s_waitcnt vmcnt(16)
	ds_write_b32 v19, v47 offset:3960
	s_waitcnt vmcnt(15)
	ds_write_b32 v19, v48 offset:4224
	s_waitcnt vmcnt(14)
	ds_write_b32 v19, v49 offset:4488
	s_waitcnt vmcnt(13)
	ds_write_b32 v19, v50 offset:4752
	s_waitcnt vmcnt(12)
	ds_write_b32 v19, v51 offset:5016
	s_waitcnt vmcnt(11)
	ds_write_b32 v19, v52 offset:5280
	s_waitcnt vmcnt(10)
	ds_write_b32 v19, v53 offset:5544
	s_waitcnt vmcnt(9)
	ds_write_b32 v19, v54 offset:5808
	s_waitcnt vmcnt(8)
	ds_write_b32 v19, v55 offset:6072
	s_waitcnt vmcnt(7)
	ds_write_b32 v19, v56 offset:6336
	s_waitcnt vmcnt(6)
	ds_write_b32 v19, v57 offset:6600
	s_waitcnt vmcnt(5)
	ds_write_b32 v19, v58 offset:6864
	s_waitcnt vmcnt(4)
	ds_write_b32 v19, v59 offset:7128
	s_waitcnt vmcnt(3)
	ds_write_b32 v19, v60 offset:7392
	s_waitcnt vmcnt(2)
	ds_write_b32 v19, v61 offset:7656
	s_waitcnt vmcnt(1)
	ds_write_b32 v19, v62 offset:7920
	s_waitcnt vmcnt(0)
	ds_write_b32 v19, v63 offset:8184
	s_mul_i32 s0, s101, 0x2c000
	s_lshl_b32 s1, s100, 7
	s_add_u32 s0, s0, s1
	s_add_u32 s0, s34, s0
	s_addc_u32 s1, s35, 0
	s_waitcnt lgkmcnt(0)
	ds_read_b32 v64, v22
	ds_read_b32 v65, v22 offset:132
	ds_read_b32 v66, v22 offset:264
	ds_read_b32 v67, v22 offset:396
	ds_read_b32 v68, v22 offset:528
	ds_read_b32 v69, v22 offset:660
	ds_read_b32 v70, v22 offset:792
	ds_read_b32 v71, v22 offset:924
	ds_read_b32 v72, v22 offset:32
	ds_read_b32 v73, v22 offset:164
	ds_read_b32 v74, v22 offset:296
	ds_read_b32 v75, v22 offset:428
	ds_read_b32 v76, v22 offset:560
	ds_read_b32 v77, v22 offset:692
	ds_read_b32 v78, v22 offset:824
	ds_read_b32 v79, v22 offset:956
	ds_read_b32 v80, v22 offset:64
	ds_read_b32 v81, v22 offset:196
	ds_read_b32 v82, v22 offset:328
	ds_read_b32 v83, v22 offset:460
	ds_read_b32 v84, v22 offset:592
	ds_read_b32 v85, v22 offset:724
	ds_read_b32 v86, v22 offset:856
	ds_read_b32 v87, v22 offset:988
	ds_read_b32 v88, v22 offset:96
	ds_read_b32 v89, v22 offset:228
	ds_read_b32 v90, v22 offset:360
	ds_read_b32 v91, v22 offset:492
	ds_read_b32 v92, v22 offset:624
	ds_read_b32 v93, v22 offset:756
	ds_read_b32 v94, v22 offset:888
	ds_read_b32 v95, v22 offset:1020
	s_waitcnt lgkmcnt(15)
	v_cvt_pk_bf16_f32 v96, v64, v65
	v_cvt_pk_bf16_f32 v97, v66, v67
	v_cvt_pk_bf16_f32 v98, v68, v69
	v_cvt_pk_bf16_f32 v99, v70, v71
	global_store_dwordx4 v24, v[96:99], s[0:1]
	s_add_u32 s0, s0, 0xb000
	s_addc_u32 s1, s1, 0
	s_waitcnt lgkmcnt(15)
	v_cvt_pk_bf16_f32 v100, v72, v73
	v_cvt_pk_bf16_f32 v101, v74, v75
	v_cvt_pk_bf16_f32 v102, v76, v77
	v_cvt_pk_bf16_f32 v103, v78, v79
	global_store_dwordx4 v24, v[100:103], s[0:1]
	s_add_u32 s0, s0, 0xb000
	s_addc_u32 s1, s1, 0
	s_waitcnt lgkmcnt(8)
	v_cvt_pk_bf16_f32 v104, v80, v81
	v_cvt_pk_bf16_f32 v105, v82, v83
	v_cvt_pk_bf16_f32 v106, v84, v85
	v_cvt_pk_bf16_f32 v107, v86, v87
	global_store_dwordx4 v24, v[104:107], s[0:1]
	s_add_u32 s0, s0, 0xb000
	s_addc_u32 s1, s1, 0
	s_waitcnt lgkmcnt(0)
	v_cvt_pk_bf16_f32 v108, v88, v89
	v_cvt_pk_bf16_f32 v109, v90, v91
	v_cvt_pk_bf16_f32 v110, v92, v93
	v_cvt_pk_bf16_f32 v111, v94, v95
	global_store_dwordx4 v24, v[108:111], s[0:1]
	s_add_i32 s98, s98, 0x400
	s_cmpk_lt_u32 s98, 0x580
	s_cbranch_scc1 .Ltr_loop_a
	s_mov_b64 exec, s[38:39]
.Ltr_done_a:
.LBB0_977:
	s_waitcnt vmcnt(0)
	s_waitcnt lgkmcnt(0)
	s_barrier
	s_and_saveexec_b64 s[0:1], s[84:85]
	s_cbranch_execz .LBB0_1029
	s_add_i32 s4, 0, 0x20040
	v_mov_b32_e32 v0, s4
	s_waitcnt vmcnt(0) expcnt(0) lgkmcnt(0)
	ds_read_b32 v2, v0
	s_add_i32 s4, 0, 0x20044
	v_mov_b32_e32 v0, s4
	ds_read_b32 v0, v0
	s_waitcnt lgkmcnt(1)
	v_cmp_ne_u32_e32 vcc, 0, v2
	s_cbranch_vccnz .LBB0_993
	s_add_u32 s4, s76, 0x60200
	s_addc_u32 s5, s77, 0
	s_add_u32 s6, s76, 0x60400
	s_addc_u32 s7, s77, 0
	s_add_u32 s8, s76, 0x60500
	s_addc_u32 s9, s77, 0
	s_add_u32 s10, s76, 0x60600
	s_addc_u32 s11, s77, 0
	s_add_u32 s12, s76, 0x60700
	s_addc_u32 s13, s77, 0
	s_add_u32 s14, s76, 0x60800
	s_addc_u32 s15, s77, 0
	s_add_u32 s16, s76, 0x60900
	s_addc_u32 s17, s77, 0
	s_add_u32 s18, s76, 0x60a00
	s_addc_u32 s19, s77, 0
	s_add_u32 s20, s76, 0x60b00
	s_addc_u32 s21, s77, 0
	s_add_u32 s22, s76, 0x60c00
	s_addc_u32 s23, s77, 0
	s_add_u32 s24, s76, 0x60d00
	s_addc_u32 s25, s77, 0
	s_add_u32 s26, s76, 0x60e00
	s_addc_u32 s27, s77, 0
	s_add_u32 s28, s76, 0x60f00
	s_addc_u32 s29, s77, 0
	s_add_u32 s30, s76, 0x61000
	s_addc_u32 s31, s77, 0
	s_add_u32 s34, s76, 0x61100
	s_addc_u32 s35, s77, 0
	s_add_u32 s36, s76, 0x61200
	s_addc_u32 s37, s77, 0
	s_mul_i32 s33, s79, s82
	s_add_u32 s38, s76, 0x61300
	s_mul_i32 s33, s33, s78
	s_addc_u32 s39, s77, 0
	s_mov_b32 s46, 1
	v_mov_b32_e32 v16, 0
	s_branch .LBB0_981

; #define LAS __attribute__((address_space(3)))
; __device__ __forceinline__ unsigned cvt_pk_bf16(float lo, float hi) { unsigned r; asm volatile("v_cvt_pk_bf16_f32 %0, %1, %2" : "=v"(r) : "v"(lo), "v"(hi)); return r; }
; #define ST16(grp, p, v) do { if ((NTG >> (grp)) & 1) NT16(p, v); else PL16(p, v); } while (0)
; __device__ __forceinline__ void transpose_item(const float* W, int K, int N, bf16_t* WT, int n0src, int n0dst, int k0, LAS float* scr, int lane) {
;     float v[32];
; #pragma unroll
;     for (int i = 0; i < 32; ++i) { const int kk = 2 * i + (lane >> 5); v[i] = W[(size_t)(k0 + kk) * N + n0src + (lane & 31)]; }
; #pragma unroll
;     for (int i = 0; i < 32; ++i) { const int kk = 2 * i + (lane >> 5); scr[kk * 33 + (lane & 31)] = v[i]; }
;     asm volatile("s_waitcnt lgkmcnt(0)" ::: "memory");
;     const int c = lane & 7;
; #pragma unroll
;     for (int j = 0; j < 4; ++j) { const int n = (lane >> 3) + 8 * j; const LAS float* s = scr + (8 * c) * 33 + n;
;         u32x4 o; o.x = cvt_pk_bf16(s[0 * 33], s[1 * 33]); o.y = cvt_pk_bf16(s[2 * 33], s[3 * 33]); o.z = cvt_pk_bf16(s[4 * 33], s[5 * 33]); o.w = cvt_pk_bf16(s[6 * 33], s[7 * 33]);
;         ST16(6, WT + (size_t)(n0dst + n) * K + k0 + 8 * c, o); }
;     asm volatile("s_waitcnt lgkmcnt(0)" ::: "memory");
; }
; __device__ __forceinline__ void prologue(const Params& p, LAS unsigned char* lds) {
;     ...
;             if (r < 4 * I_W2) { const int mi = r / I_W2; r -= mi * I_W2; const int kb = r / 32, nb = r % 32;
;                 transpose_item(p.in[I_FFNWOUT] + (size_t)mi * DFF * D, DFF, D, (bf16_t*)(ws + WS_W2T + mi * SZ_W2T), nb * 32, nb * 32, kb * 64, scr, lane); continue; }
.LBB0_1141:
	s_waitcnt vmcnt(0)
	s_barrier
	s_cmpk_lg_u32 s78, 0x100
	s_cbranch_scc1 .Ltr_done_b
	s_cmpk_lt_u32 s68, 0x80
	s_cbranch_scc1 .Ltr_done_b
	s_mov_b64 s[38:39], exec
	s_mov_b64 exec, -1
	v_readfirstlane_b32 s99, v176
	s_lshr_b32 s99, s99, 6
	s_sub_i32 s98, s68, 0x80
	s_lshl_b32 s98, s98, 3
	s_add_i32 s98, s98, s99
	s_lshl_b32 s99, s99, 14
	v_and_b32_e32 v16, 63, v176
	v_and_b32_e32 v17, 31, v16
	v_lshrrev_b32_e32 v18, 5, v16
	v_mul_u32_u24_e32 v19, 0x84, v18
	v_lshl_add_u32 v19, v17, 2, v19
	v_add_u32_e32 v19, s99, v19
	v_and_b32_e32 v20, 7, v16
	v_lshrrev_b32_e32 v21, 3, v16
	v_mul_u32_u24_e32 v22, 0x420, v20
	v_lshl_add_u32 v22, v21, 2, v22
	v_add_u32_e32 v22, s99, v22
	v_lshlrev_b32_e32 v23, 12, v18
	v_lshl_add_u32 v23, v17, 2, v23
	v_mul_u32_u24_e32 v24, 0x1600, v21
	v_lshl_add_u32 v24, v20, 4, v24
	v_readlane_b32 s32, v253, 0
	v_readlane_b32 s33, v253, 1
	s_add_u32 s32, s32, 0x1600000
	s_addc_u32 s33, s33, 0
	s_add_u32 s34, s76, 0x3900000
	s_addc_u32 s35, s77, 0

; __device__ __forceinline__ void xcd_barrier(const XcdBarrier& b) {
;     asm volatile("s_waitcnt vmcnt(0)" ::: "memory");
;     __syncthreads();
;     if (threadIdx.x == 0) {
;         unsigned* bar = b.bar;
;         __builtin_amdgcn_s_waitcnt(0);
;         unsigned nloc = b.st[0], nx = b.st[1];
;         if (nloc == 0u) { xcd_barrier_complete(bar, b.x, nloc, nx); b.st[0] = nloc; b.st[1] = nx; }
.Ltr_done_b:
.LBB0_1142:
	s_waitcnt vmcnt(0)
	s_waitcnt lgkmcnt(0)
	s_barrier
	s_and_saveexec_b64 s[0:1], s[84:85]
	s_cbranch_execz .LBB0_1194
	s_add_i32 s2, 0, 0x20040
	v_mov_b32_e32 v0, s2
	s_waitcnt vmcnt(0) expcnt(0) lgkmcnt(0)
	ds_read_b32 v2, v0
	s_add_i32 s2, 0, 0x20044
	v_mov_b32_e32 v0, s2
	ds_read_b32 v0, v0
	s_waitcnt lgkmcnt(1)
	v_cmp_ne_u32_e32 vcc, 0, v2
	s_cbranch_vccnz .LBB0_1158
	s_add_u32 s2, s76, 0x60200
	s_addc_u32 s3, s77, 0
	s_add_u32 s4, s76, 0x60400
	s_addc_u32 s5, s77, 0
	s_add_u32 s8, s76, 0x60500
	s_addc_u32 s9, s77, 0
	s_add_u32 s10, s76, 0x60600
	s_addc_u32 s11, s77, 0
	s_add_u32 s12, s76, 0x60700
	s_addc_u32 s13, s77, 0
	s_add_u32 s14, s76, 0x60800
	s_addc_u32 s15, s77, 0
	s_add_u32 s16, s76, 0x60900
	s_addc_u32 s17, s77, 0
	s_add_u32 s18, s76, 0x60a00
	s_addc_u32 s19, s77, 0
	s_add_u32 s20, s76, 0x60b00
	s_addc_u32 s21, s77, 0
	s_add_u32 s22, s76, 0x60c00
	s_addc_u32 s23, s77, 0
	s_add_u32 s24, s76, 0x60d00
	s_addc_u32 s25, s77, 0
	s_add_u32 s26, s76, 0x60e00
	s_addc_u32 s27, s77, 0
	s_add_u32 s28, s76, 0x60f00
	s_addc_u32 s29, s77, 0
	s_add_u32 s30, s76, 0x61000
	s_addc_u32 s31, s77, 0
	s_add_u32 s34, s76, 0x61100
	s_addc_u32 s35, s77, 0
	s_add_u32 s36, s76, 0x61200
	s_addc_u32 s37, s77, 0
	s_mul_i32 s33, s79, s82
	s_add_u32 s38, s76, 0x61300
	s_mul_i32 s33, s33, s78
	s_addc_u32 s39, s77, 0
	s_mov_b32 s46, 1
	v_mov_b32_e32 v16, 0
	s_branch .LBB0_1146

; #define LAS __attribute__((address_space(3)))
; __device__ __forceinline__ unsigned cvt_pk_bf16(float lo, float hi) { unsigned r; asm volatile("v_cvt_pk_bf16_f32 %0, %1, %2" : "=v"(r) : "v"(lo), "v"(hi)); return r; }
; #define ST16(grp, p, v) do { if ((NTG >> (grp)) & 1) NT16(p, v); else PL16(p, v); } while (0)
; __device__ __forceinline__ void transpose_item(const float* W, int K, int N, bf16_t* WT, int n0src, int n0dst, int k0, LAS float* scr, int lane) {
;     float v[32];
; #pragma unroll
;     for (int i = 0; i < 32; ++i) { const int kk = 2 * i + (lane >> 5); v[i] = W[(size_t)(k0 + kk) * N + n0src + (lane & 31)]; }
; #pragma unroll
;     for (int i = 0; i < 32; ++i) { const int kk = 2 * i + (lane >> 5); scr[kk * 33 + (lane & 31)] = v[i]; }
;     asm volatile("s_waitcnt lgkmcnt(0)" ::: "memory");
;     const int c = lane & 7;
; #pragma unroll
;     for (int j = 0; j < 4; ++j) { const int n = (lane >> 3) + 8 * j; const LAS float* s = scr + (8 * c) * 33 + n;
;         u32x4 o; o.x = cvt_pk_bf16(s[0 * 33], s[1 * 33]); o.y = cvt_pk_bf16(s[2 * 33], s[3 * 33]); o.z = cvt_pk_bf16(s[4 * 33], s[5 * 33]); o.w = cvt_pk_bf16(s[6 * 33], s[7 * 33]);
;         ST16(6, WT + (size_t)(n0dst + n) * K + k0 + 8 * c, o); }
;     asm volatile("s_waitcnt lgkmcnt(0)" ::: "memory");
; }
; __device__ __forceinline__ void prologue(const Params& p, LAS unsigned char* lds) {
;     ...
;             if (r < 4 * I_W2) { const int mi = r / I_W2; r -= mi * I_W2; const int kb = r / 32, nb = r % 32;
;                 transpose_item(p.in[I_FFNWOUT] + (size_t)mi * DFF * D, DFF, D, (bf16_t*)(ws + WS_W2T + mi * SZ_W2T), nb * 32, nb * 32, kb * 64, scr, lane); continue; }
.LBB0_1562:
	s_waitcnt vmcnt(0)
	s_barrier
	s_cmpk_lg_u32 s78, 0x100
	s_cbranch_scc1 .Ltr_done_c
	s_cmpk_lt_u32 s68, 0x80
	s_cbranch_scc1 .Ltr_done_c
	s_mov_b64 s[38:39], exec
	s_mov_b64 exec, -1
	v_readfirstlane_b32 s99, v176
	s_lshr_b32 s99, s99, 6
	s_sub_i32 s98, s68, 0x80
	s_lshl_b32 s98, s98, 3
	s_add_i32 s98, s98, s99
	s_lshl_b32 s99, s99, 14
	v_and_b32_e32 v16, 63, v176
	v_and_b32_e32 v17, 31, v16
	v_lshrrev_b32_e32 v18, 5, v16
	v_mul_u32_u24_e32 v19, 0x84, v18
	v_lshl_add_u32 v19, v17, 2, v19
	v_add_u32_e32 v19, s99, v19
	v_and_b32_e32 v20, 7, v16
	v_lshrrev_b32_e32 v21, 3, v16
	v_mul_u32_u24_e32 v22, 0x420, v20
	v_lshl_add_u32 v22, v21, 2, v22
	v_add_u32_e32 v22, s99, v22
	v_lshlrev_b32_e32 v23, 12, v18
	v_lshl_add_u32 v23, v17, 2, v23
	v_mul_u32_u24_e32 v24, 0x1600, v21
	v_lshl_add_u32 v24, v20, 4, v24
	v_readlane_b32 s32, v253, 0
	v_readlane_b32 s33, v253, 1
	s_add_u32 s32, s32, 0x2100000
	s_addc_u32 s33, s33, 0
	s_add_u32 s34, s76, 0x3e80000
	s_addc_u32 s35, s77, 0

; __device__ __forceinline__ void xcd_barrier(const XcdBarrier& b) {
;     asm volatile("s_waitcnt vmcnt(0)" ::: "memory");
;     __syncthreads();
;     if (threadIdx.x == 0) {
;         unsigned* bar = b.bar;
;         __builtin_amdgcn_s_waitcnt(0);
;         unsigned nloc = b.st[0], nx = b.st[1];
;         if (nloc == 0u) { xcd_barrier_complete(bar, b.x, nloc, nx); b.st[0] = nloc; b.st[1] = nx; }
.Ltr_done_c:
.LBB0_1563:
	s_waitcnt vmcnt(0)
	s_waitcnt lgkmcnt(0)
	s_barrier
	s_and_saveexec_b64 s[0:1], s[84:85]
	s_cbranch_execz .LBB0_1615
	s_add_i32 s2, 0, 0x20040
	v_mov_b32_e32 v0, s2
	s_waitcnt vmcnt(0) expcnt(0) lgkmcnt(0)
	ds_read_b32 v2, v0
	s_add_i32 s2, 0, 0x20044
	v_mov_b32_e32 v0, s2
	ds_read_b32 v0, v0
	s_waitcnt lgkmcnt(1)
	v_cmp_ne_u32_e32 vcc, 0, v2
	s_cbranch_vccnz .LBB0_1579
	s_add_u32 s2, s76, 0x60200
	s_addc_u32 s3, s77, 0
	s_add_u32 s4, s76, 0x60400
	s_addc_u32 s5, s77, 0
	s_add_u32 s6, s76, 0x60500
	s_addc_u32 s7, s77, 0
	s_add_u32 s8, s76, 0x60600
	s_addc_u32 s9, s77, 0
	s_add_u32 s10, s76, 0x60700
	s_addc_u32 s11, s77, 0
	s_add_u32 s12, s76, 0x60800
	s_addc_u32 s13, s77, 0
	s_add_u32 s14, s76, 0x60900
	s_addc_u32 s15, s77, 0
	s_add_u32 s16, s76, 0x60a00
	s_addc_u32 s17, s77, 0
	s_add_u32 s18, s76, 0x60b00
	s_addc_u32 s19, s77, 0
	s_add_u32 s20, s76, 0x60c00
	s_addc_u32 s21, s77, 0
	s_add_u32 s22, s76, 0x60d00
	s_addc_u32 s23, s77, 0
	s_add_u32 s24, s76, 0x60e00
	s_addc_u32 s25, s77, 0
	s_add_u32 s26, s76, 0x60f00
	s_addc_u32 s27, s77, 0
	s_add_u32 s28, s76, 0x61000
	s_addc_u32 s29, s77, 0
	s_add_u32 s30, s76, 0x61100
	s_addc_u32 s31, s77, 0
	s_add_u32 s34, s76, 0x61200
	s_addc_u32 s35, s77, 0
	s_mul_i32 s33, s79, s82
	s_add_u32 s36, s76, 0x61300
	s_mul_i32 s33, s33, s78
	s_addc_u32 s37, s77, 0
	s_mov_b32 s44, 1
	v_mov_b32_e32 v16, 0
	s_branch .LBB0_1567
